# P4 queue order table: pure longest-first by measured item durations (s5y output items before the small attention units)
# baseline (speedup 1.0000x reference)
; __global__ void __launch_bounds__(512, 2) fwd_kernel(Args A0) {
;     ...
;           static constexpr unsigned char ORD[108] = {60, 61, 62, 63, 56, 57, 58, 59, 52, 53, 54, 55, 48, 49, 50, 51, 44, 45, 46, 47, 40, 41, 42, 43, 36, 37, 38, 39, 32, 33, 34, 35, 28, 29, 30, 31, 64, 65, 66, 67, 68, 69, 70, 71, 72, 73, 74, 75, 24, 76, 77, 25, 78, 79, 26, 80, 81, 27, 82, 83, 20, 84, 85, 21, 86, 87, 22, 88, 89, 23, 90, 91, 16, 92, 93, 17, 94, 95, 18, 96, 97, 19, 98, 99, 12, 100, 101, 13, 102, 103, 14, 104, 105, 15, 106, 107, 8, 9, 10, 11, 4, 5, 6, 7, 0, 1, 2, 3};
;           const int oc = ORD[li];
_ZZ10fwd_kernel4ArgsE3ORD.const:
	.ascii	"\074\075\076\077\070\071\072\073\064\065\066\067\060\061\062\063\054\055\056\057\050\051\052\053\044\045\046\047\040\041\042\043\034\035\036\037\030\031\032\033\024\025\026\027\100\101\102\103\104\105\106\107\020\021\022\023\114\115\116\117\120\121\122\123\124\125\126\127\130\131\132\133\134\135\136\137\140\141\142\143\144\145\146\147\150\151\152\153\014\015\016\017\010\011\012\013\004\005\006\007\000\001\002\003\110\111\112\113"
	.size	_ZZ10fwd_kernel4ArgsE3ORD.const, 108

; __global__ void __launch_bounds__(512, 2) fwd_kernel(Args A0) {
;     ...
;           static constexpr unsigned char ORD[108] = {60, 61, 62, 63, 56, 57, 58, 59, 52, 53, 54, 55, 48, 49, 50, 51, 44, 45, 46, 47, 40, 41, 42, 43, 36, 37, 38, 39, 32, 33, 34, 35, 28, 29, 30, 31, 64, 65, 66, 67, 68, 69, 70, 71, 72, 73, 74, 75, 24, 76, 77, 25, 78, 79, 26, 80, 81, 27, 82, 83, 20, 84, 85, 21, 86, 87, 22, 88, 89, 23, 90, 91, 16, 92, 93, 17, 94, 95, 18, 96, 97, 19, 98, 99, 12, 100, 101, 13, 102, 103, 14, 104, 105, 15, 106, 107, 8, 9, 10, 11, 4, 5, 6, 7, 0, 1, 2, 3};
	.type	__hip_cuid_af2ee39715b257f4,@object
